# v14: phase-2 gate scan: the three cross-row shuffles per 16-token block done with v_permlane16/32_swap instead of ds_bpermute round trips
# baseline (speedup 1.0000x reference)
; #define LAS __attribute__((address_space(3)))
; __device__ __forceinline__ void phase_gla_pre(const Params& P, LAS unsigned char* lds, bool dry) {
;     const int tid = opaque_tid(), lane = tid & 63, w = tid >> 6, fr = lane & 15, g = lane >> 4;
;     bf16_t* PJ = (bf16_t*)(P.ws + WS_PJ); const float* LR = (const float*)(P.ws + WS_LR); float* DEC = (float*)(P.ws + WS_DEC); bf16_t* PB = (bf16_t*)(P.ws + WS_PB);
;     constexpr int QP = 272, BP = 528, O_KI = 64 * QP, O_B = 2 * 64 * QP, O_LR = O_B + 64 * BP;
;     LAS unsigned char* Lqi = lds; LAS unsigned char* Lki = lds + O_KI; LAS unsigned char* Lb = lds + O_B; LAS float* Llr = (LAS float*)(lds + O_LR);
;     const int te = tid >> 3, kc = tid & 7;
;     u32x4 rq[2], rk[2]; f32x4 rl = (f32x4){0.f, 0.f, 0.f, 0.f};
;     int item = blockIdx.x;
;     if (item < 2048) {
;         const int bh = item >> 6, row0 = (bh >> 2) * SEQ + (item & 63) * 64; const bf16_t* p_ = PJ + ((size_t)bh * SEQ + (item & 63) * 64 + te) * 128 + 16 * kc;
;         rq[0] = *(const u32x4*)(p_ + T_Q); rq[1] = *(const u32x4*)(p_ + T_Q + 8); rk[0] = *(const u32x4*)(p_ + T_K); rk[1] = *(const u32x4*)(p_ + T_K + 8);
;         if (tid < 256) rl = *(const f32x4*)(LR + (size_t)row0 * 16 + 4 * tid);
;     }
;     for (; item < 2048; item += gridDim.x) {
;         const int bh = item >> 6, c = item & 63, b = bh >> 2, h = bh & 3, row0 = b * SEQ + c * 64;
;         if (tid < 256) *(LAS f32x4*)(Llr + 4 * tid) = rl;
;         bf16x8 bhi = (bf16x8){0, 0, 0, 0, 0, 0, 0, 0}, blo = bhi;
;         if (g < 2) { f32x4 w0, w1;
; #pragma unroll
;             for (int j = 0; j < 4; ++j) { w0[j] = P.w_gate_up[(8 * g + j) * 512 + h * 128 + 16 * w + fr]; w1[j] = P.w_gate_up[(8 * g + 4 + j) * 512 + h * 128 + 16 * w + fr]; }
;             split8(w0, w1, bhi, blo); }
;         const float bg = P.b_gate_up[h * 128 + 16 * w + fr];
;     ...
;         const int tt = w >> 1;
; #pragma unroll
;         for (int s2i = 0; s2i < 2; ++s2i) {
;             const int st = 2 * (w & 1) + s2i; f32x4 acc = (f32x4){0.f, 0.f, 0.f, 0.f};
;             if (st <= tt) {
; #pragma unroll
;                 for (int ks = 0; ks < 4; ++ks) acc = __builtin_amdgcn_mfma_f32_16x16x32_bf16(rowfrag(Lki, QP, 16 * st, 64 * ks, g, fr), rowfrag(Lqi, QP, 16 * tt, 64 * ks, g, fr), acc, 0, 0, 0);
;             }
;             const int t = 16 * tt + fr, sb = 16 * st + 4 * g;
.LBB0_478:
	s_or_b64 exec, exec, s[6:7]
	v_mbcnt_hi_u32_b32 v30, -1, v195
	v_add_u32_e32 v31, -16, v30
	v_and_b32_e32 v32, 64, v30
	v_cmp_lt_i32_e32 vcc, v31, v32
	v_lshlrev_b32_e32 v50, 1, v21
	v_mov_b32_e32 v51, 0
	v_cndmask_b32_e32 v31, v31, v30, vcc
	v_lshlrev_b32_e32 v83, 2, v31
	v_subrev_u32_e32 v31, 32, v30
	v_ashrrev_i32_e32 v26, 6, v24
	v_and_b32_e32 v27, 15, v24
	v_cmp_lt_i32_e32 vcc, v31, v32
	v_lshl_add_u64 v[52:53], s[44:45], 0, v[50:51]
	v_lshlrev_b32_e32 v50, 2, v21
	v_ashrrev_i32_e32 v21, 7, v24
	v_lshl_or_b32 v81, v26, 4, v27
	v_cndmask_b32_e32 v30, v31, v30, vcc
	s_add_i32 s3, 0, 0x10c00
	v_lshl_add_u64 v[56:57], v[22:23], 2, s[76:77]
	v_lshlrev_b32_e32 v22, 1, v26
	v_lshl_or_b32 v26, v21, 4, v27
	v_bfe_u32 v28, v24, 4, 2
	v_lshlrev_b32_e32 v29, 4, v24
	v_lshlrev_b32_e32 v84, 2, v30
	v_or_b32_e32 v30, v32, v27
	v_lshl_add_u32 v32, v27, 6, s3
	s_movk_i32 s3, 0x210
	v_and_b32_e32 v24, 2, v22
	v_lshlrev_b32_e32 v22, 6, v26
	v_mul_lo_u32 v34, v48, s3
	v_ashrrev_i32_e32 v23, 31, v22
	s_movk_i32 s3, 0x110
	v_mov_b32_e32 v31, 0xc0
	v_lshl_add_u64 v[58:59], v[22:23], 1, s[72:73]
	v_mul_lo_u32 v22, v26, s3
	v_lshl_or_b32 v85, v30, 2, v31
	v_lshlrev_b32_e32 v30, 2, v28
	v_add_u32_e32 v35, 0, v22
	v_lshlrev_b32_e32 v22, 4, v24
	v_cmp_le_i32_e64 s[14:15], v24, v21
	v_or_b32_e32 v39, v22, v27
	v_cmp_lt_i32_e64 s[16:17], v24, v21
	v_or_b32_e32 v21, 16, v22
	v_or_b32_e32 v22, v22, v30
	v_or_b32_e32 v24, v21, v27
	v_or_b32_e32 v27, 2, v22
	v_cmp_gt_i32_e64 s[22:23], v27, v26
	v_or_b32_e32 v27, 3, v22
	v_or_b32_e32 v21, v21, v30
	v_add_u32_e32 v86, 0, v34
	v_lshlrev_b32_e32 v87, 6, v25
	v_lshlrev_b32_e32 v25, 8, v48
	v_lshlrev_b32_e32 v23, 4, v28
	v_cmp_gt_i32_e64 s[24:25], v27, v26
	v_cmp_gt_i32_e64 s[26:27], v21, v26
	v_cmp_lt_i32_e64 s[28:29], v21, v26
	v_or_b32_e32 v27, 2, v21
	v_or_b32_e32 v21, 3, v21
	v_cmp_gt_u32_e64 s[6:7], 2, v28
	v_lshlrev_b32_e32 v80, 12, v28
	v_cmp_eq_u32_e64 s[8:9], 0, v28
	v_cmp_lt_u32_e64 s[10:11], 1, v28
	v_lshl_add_u32 v31, v81, 2, 0
	v_lshlrev_b32_e32 v33, 5, v28
	v_sub_u32_e32 v25, v86, v25
	v_add_u32_e32 v34, 0, v23
	v_mul_u32_u24_e32 v28, 0x840, v28
	v_or_b32_e32 v36, 16, v87
	v_or_b32_e32 v37, 32, v87
	v_or_b32_e32 v38, 48, v87
	v_mul_u32_u24_e32 v39, 0x110, v39
	v_mul_u32_u24_e32 v24, 0x110, v24
	v_cmp_gt_i32_e64 s[34:35], v21, v26
	s_add_i32 s36, s2, s38
	v_add_u32_e32 v21, 0, v29
	s_add_i32 s94, 0, 0x109f0
	v_add_u32_e32 v82, 0x800, v81
	v_cmp_eq_u32_e64 s[12:13], 63, v48
	v_lshl_add_u64 v[54:55], s[50:51], 0, v[50:51]
	v_cmp_gt_i32_e64 s[18:19], v22, v26
	v_cmp_lt_i32_e64 s[20:21], v22, v26
	v_cmp_gt_i32_e64 s[30:31], v27, v26
	s_lshl_b32 s3, s38, 6
	s_lshl_b32 s84, s36, 4
	s_lshl_b32 s85, s38, 4
	v_add_u32_e32 v88, 0x10c00, v21
	s_movk_i32 s86, 0x7fff
	s_mov_b32 s87, 0xffff0000
	s_mov_b32 s88, 0x7060302
	s_mov_b32 s89, 0xbfb8aa3b
	s_mov_b32 s90, 0x800000
	s_mov_b32 s91, 0x3f317217
	s_mov_b32 s92, 0x7f800000
	s_mov_b32 s93, 0x3d800000
	s_mov_b32 s96, 0
	s_mov_b32 s97, 0xffff
	v_add_u32_e32 v89, s94, v36
	v_add_u32_e32 v90, s94, v37
	v_add_u32_e32 v91, s94, v38
	v_add_u32_e32 v92, v25, v20
	s_mov_b32 s95, 0xa000000
	s_mov_b64 s[76:77], 0x8000000
	s_mov_b64 s[78:79], 0xa000000
	v_add_u32_e32 v93, v34, v39
	v_lshlrev_b32_e32 v50, 1, v22
	v_add_u32_e32 v94, v34, v24
	v_mov_b32_e32 v95, 1
	v_add_u32_e32 v96, v32, v33
	v_mov_b32_e32 v97, 0x41b17218
	v_add_u32_e32 v98, v31, v28
	v_add_u32_e32 v99, v35, v23
	s_mov_b32 s80, s2
	s_branch .LBB0_480

; #define LAS __attribute__((address_space(3)))
; __device__ __forceinline__ void phase_gla_pre(const Params& P, LAS unsigned char* lds, bool dry) {
;     ...
;             if (g < 2) { const f32x4 l0 = *(const LAS f32x4*)(Llr + (16 * tt + fr) * 16 + 8 * g), l1 = *(const LAS f32x4*)(Llr + (16 * tt + fr) * 16 + 8 * g + 4); split8(l0, l1, ahi, alo); }
;             f32x4 acc = (f32x4){bg, bg, bg, bg};
;             acc = __builtin_amdgcn_mfma_f32_16x16x32_bf16(alo, bhi, acc, 0, 0, 0); acc = __builtin_amdgcn_mfma_f32_16x16x32_bf16(ahi, blo, acc, 0, 0, 0); acc = __builtin_amdgcn_mfma_f32_16x16x32_bf16(ahi, bhi, acc, 0, 0, 0);
;             float pr[4];
; #pragma unroll
;             for (int r = 0; r < 4; ++r) { const float lg = acc[r]; const float ls = fminf(lg, 0.f) - __logf(1.0f + __expf(-fabsf(lg))); pr[r] = ls * (1.0f / 16.0f) + (r ? pr[r - 1] : 0.f); }
;             const float T = pr[3];
;             const float u1 = __shfl_up(T, 16), s1 = T + (g >= 1 ? u1 : 0.f);
;             const float u2 = __shfl_up(s1, 32), s2 = s1 + (g >= 2 ? u2 : 0.f);
;             const float base = run + (s2 - T); run += __shfl(s2, 48 + fr);
; #pragma unroll
;             for (int r = 0; r < 4; ++r) *(LAS float*)(Lb + (16 * tt + 4 * g + r) * BP + (16 * w + fr) * 4) = base + pr[r];
.Lp2_nowait1:
	v_mov_b32_e32 v140, v20
	v_mov_b32_e32 v141, v21
	v_mov_b32_e32 v142, v22
	v_mov_b32_e32 v143, v23
	v_mov_b32_e32 v144, v24
	v_mov_b32_e32 v145, v25
	v_mov_b32_e32 v146, v26
	v_mov_b32_e32 v147, v27
	v_mov_b32_e32 v148, v28
	s_and_b32 s98, s38, 0xff
	s_cselect_b32 s98, 0, 1
	v_mov_b32_e32 v29, v28
	v_mov_b32_e32 v30, v28
	v_mov_b32_e32 v31, v28
	v_mov_b32_e32 v40, 0
	v_mov_b32_e32 v41, 0
	v_mfma_f32_16x16x32_bf16 v[32:35], v[32:35], v[20:23], v[28:31]
	v_mfma_f32_16x16x32_bf16 v[32:35], v[36:39], v[24:27], v[32:35]
	v_mfma_f32_16x16x32_bf16 v[32:35], v[36:39], v[20:23], v[32:35]
	s_nop 7
	v_max_f32_e32 v36, v32, v32
	v_mul_f32_e64 v32, |v32|, s89
	v_exp_f32_e32 v32, v32
	v_mul_f32_e64 v37, |v33|, s89
	v_exp_f32_e32 v37, v37
	v_min_f32_e32 v36, 0, v36
	v_add_f32_e32 v32, 1.0, v32
	v_add_f32_e32 v37, 1.0, v37
	v_log_f32_e32 v32, v32
	v_log_f32_e32 v37, v37
	v_mul_f32_e32 v39, 0x3f317217, v32
	v_fma_f32 v39, v32, s91, -v39
	v_fmac_f32_e32 v39, 0x3377d1cf, v32
	v_fmac_f32_e32 v39, 0x3f317217, v32
	v_max_f32_e32 v33, v33, v33
	v_min_f32_e32 v33, 0, v33
	v_mov_b32_e32 v32, v39
	v_sub_f32_e32 v32, v36, v32
	v_mul_f32_e32 v36, 0x3f317217, v37
	v_fma_f32 v36, v37, s91, -v36
	v_fmac_f32_e32 v36, 0x3377d1cf, v37
	v_fmac_f32_e32 v36, 0x3f317217, v37
	v_fma_f32 v32, v32, s93, 0
	v_mul_f32_e64 v37, |v34|, s89
	v_exp_f32_e32 v37, v37
	v_sub_f32_e32 v33, v33, v36
	v_mov_b32_e32 v39, 0
	v_add_f32_e32 v36, 1.0, v37
	s_nop 1
	v_log_f32_e32 v36, v36
	v_fmamk_f32 v37, v33, 0x3d800000, v32
	v_max_f32_e32 v33, v34, v34
	v_mul_f32_e32 v34, 0x3f317217, v36
	v_fma_f32 v34, v36, s91, -v34
	v_fmac_f32_e32 v34, 0x3377d1cf, v36
	v_fmac_f32_e32 v34, 0x3f317217, v36
	v_min_f32_e32 v33, 0, v33
	s_nop 0
	v_mul_f32_e64 v36, |v35|, s89
	v_exp_f32_e32 v36, v36
	v_sub_f32_e32 v33, v33, v34
	v_add_u32_e32 v38, 0x8800, v98
	v_add_f32_e32 v34, 1.0, v36
	s_nop 1
	v_log_f32_e32 v34, v34
	v_fmamk_f32 v36, v33, 0x3d800000, v37
	v_max_f32_e32 v33, v35, v35
	v_min_f32_e32 v33, 0, v33
	v_mul_f32_e32 v35, 0x3f317217, v34
	v_fma_f32 v35, v34, s91, -v35
	v_fmac_f32_e32 v35, 0x3377d1cf, v34
	v_fmac_f32_e32 v35, 0x3f317217, v34
	s_nop 1
	v_mov_b32_e32 v34, v35
	v_sub_f32_e32 v33, v33, v34
	v_fmamk_f32 v34, v33, 0x3d800000, v36
	v_mov_b32_e32 v241, v34
	v_mov_b32_e32 v242, v34
	s_nop 1
	v_permlane16_swap_b32_e32 v241, v242
	v_mov_b32_e32 v243, v242
	s_nop 1
	v_permlane32_swap_b32_e32 v242, v243
	v_cndmask_b32_e64 v33, v241, v242, s[96:97]
	v_cndmask_b32_e64 v33, v33, 0, s[8:9]
	v_add_f32_e32 v33, v33, v34
	v_mov_b32_e32 v244, v33
	v_mov_b32_e32 v245, v33
	s_nop 1
	v_permlane32_swap_b32_e32 v244, v245
	v_cndmask_b32_e64 v35, 0, v244, s[10:11]
	v_add_f32_e32 v33, v35, v33
	v_sub_f32_e32 v35, v33, v34
	v_mov_b32_e32 v246, v33
	v_mov_b32_e32 v247, v33
	s_nop 1
	v_permlane32_swap_b32_e32 v246, v247
	v_mov_b32_e32 v248, v247
	s_nop 1
	v_permlane16_swap_b32_e32 v247, v248
	v_mov_b32_e32 v33, v248
	v_add_f32_e32 v35, 0, v35
	v_add_f32_e32 v32, v32, v35
	v_add_f32_e32 v37, v37, v35
	ds_write2_b32 v38, v32, v37 offset1:132
	v_add_f32_e32 v32, v36, v35
	v_add_f32_e32 v34, v34, v35
	v_add_u32_e32 v35, 0x8c00, v98
	ds_write2_b32 v35, v32, v34 offset0:8 offset1:140
	v_mov_b32_e32 v32, 0
	v_mov_b32_e32 v34, 0
	v_mov_b32_e32 v35, 0
	v_mov_b32_e32 v36, 0
	v_mov_b32_e32 v37, 0
	v_mov_b32_e32 v38, 0
	s_and_saveexec_b64 s[36:37], s[6:7]
	s_cbranch_execz .LBB0_488
	ds_read_b128 v[34:37], v96 offset:1024
	ds_read_b128 v[38:41], v96 offset:1040
	s_waitcnt lgkmcnt(1)
	v_and_b32_sdwa v42, v35, v95 dst_sel:DWORD dst_unused:UNUSED_PAD src0_sel:WORD_1 src1_sel:DWORD
	v_and_b32_sdwa v43, v34, v95 dst_sel:DWORD dst_unused:UNUSED_PAD src0_sel:WORD_1 src1_sel:DWORD
	v_add3_u32 v44, v35, v42, s86
	v_add3_u32 v45, v34, v43, s86
	v_and_b32_e32 v43, 0xffff0000, v44
	v_and_b32_e32 v42, 0xffff0000, v45
	v_cvt_pk_bf16_f32 v196, v34, v35
	v_pk_add_f32 v[34:35], v[34:35], v[42:43] neg_lo:[0,1] neg_hi:[0,1]
	v_and_b32_sdwa v42, v37, v95 dst_sel:DWORD dst_unused:UNUSED_PAD src0_sel:WORD_1 src1_sel:DWORD
	v_and_b32_sdwa v43, v36, v95 dst_sel:DWORD dst_unused:UNUSED_PAD src0_sel:WORD_1 src1_sel:DWORD
	v_add3_u32 v46, v37, v42, s86
	v_add3_u32 v47, v36, v43, s86
	v_and_b32_e32 v43, 0xffff0000, v46
	v_and_b32_e32 v42, 0xffff0000, v47
	v_cvt_pk_bf16_f32 v197, v36, v37
	v_pk_add_f32 v[36:37], v[36:37], v[42:43] neg_lo:[0,1] neg_hi:[0,1]
	s_waitcnt lgkmcnt(0)
	v_and_b32_sdwa v42, v39, v95 dst_sel:DWORD dst_unused:UNUSED_PAD src0_sel:WORD_1 src1_sel:DWORD
	v_and_b32_sdwa v43, v38, v95 dst_sel:DWORD dst_unused:UNUSED_PAD src0_sel:WORD_1 src1_sel:DWORD
	v_add3_u32 v60, v39, v42, s86
	v_add3_u32 v61, v38, v43, s86
	v_and_b32_e32 v43, 0xffff0000, v60
	v_and_b32_e32 v42, 0xffff0000, v61
	v_cvt_pk_bf16_f32 v198, v38, v39
	v_pk_add_f32 v[38:39], v[38:39], v[42:43] neg_lo:[0,1] neg_hi:[0,1]
	v_and_b32_sdwa v42, v41, v95 dst_sel:DWORD dst_unused:UNUSED_PAD src0_sel:WORD_1 src1_sel:DWORD
	v_and_b32_sdwa v43, v40, v95 dst_sel:DWORD dst_unused:UNUSED_PAD src0_sel:WORD_1 src1_sel:DWORD
	v_add3_u32 v62, v41, v42, s86
	v_add3_u32 v63, v40, v43, s86
	v_and_b32_e32 v43, 0xffff0000, v62
	v_and_b32_e32 v42, 0xffff0000, v63
	v_cvt_pk_bf16_f32 v199, v40, v41
	v_pk_add_f32 v[40:41], v[40:41], v[42:43] neg_lo:[0,1] neg_hi:[0,1]
	s_nop 0
	v_cvt_pk_bf16_f32 v193, v40, v41
	v_cvt_pk_bf16_f32 v192, v38, v39
	v_cvt_pk_bf16_f32 v191, v36, v37
	v_cvt_pk_bf16_f32 v190, v34, v35
	v_mov_b32_e32 v34, v190
	v_mov_b32_e32 v35, v191
	v_mov_b32_e32 v36, v192
	v_mov_b32_e32 v37, v193
	v_mov_b32_e32 v38, v196
	v_mov_b32_e32 v39, v197
	v_mov_b32_e32 v40, v198
	v_mov_b32_e32 v41, v199
; #define LAS __attribute__((address_space(3)))
; __device__ __forceinline__ void phase_gla_pre(const Params& P, LAS unsigned char* lds, bool dry) {
;     ...
;             if (g < 2) { const f32x4 l0 = *(const LAS f32x4*)(Llr + (16 * tt + fr) * 16 + 8 * g), l1 = *(const LAS f32x4*)(Llr + (16 * tt + fr) * 16 + 8 * g + 4); split8(l0, l1, ahi, alo); }
;             f32x4 acc = (f32x4){bg, bg, bg, bg};
;             acc = __builtin_amdgcn_mfma_f32_16x16x32_bf16(alo, bhi, acc, 0, 0, 0); acc = __builtin_amdgcn_mfma_f32_16x16x32_bf16(ahi, blo, acc, 0, 0, 0); acc = __builtin_amdgcn_mfma_f32_16x16x32_bf16(ahi, bhi, acc, 0, 0, 0);
;             float pr[4];
; #pragma unroll
;             for (int r = 0; r < 4; ++r) { const float lg = acc[r]; const float ls = fminf(lg, 0.f) - __logf(1.0f + __expf(-fabsf(lg))); pr[r] = ls * (1.0f / 16.0f) + (r ? pr[r - 1] : 0.f); }
;             const float T = pr[3];
;             const float u1 = __shfl_up(T, 16), s1 = T + (g >= 1 ? u1 : 0.f);
;             const float u2 = __shfl_up(s1, 32), s2 = s1 + (g >= 2 ? u2 : 0.f);
;             const float base = run + (s2 - T); run += __shfl(s2, 48 + fr);
; #pragma unroll
;             for (int r = 0; r < 4; ++r) *(LAS float*)(Lb + (16 * tt + 4 * g + r) * BP + (16 * w + fr) * 4) = base + pr[r];
.LBB0_488:
	s_or_b64 exec, exec, s[36:37]
	v_mfma_f32_16x16x32_bf16 v[34:37], v[34:37], v[20:23], v[28:31]
	v_mfma_f32_16x16x32_bf16 v[34:37], v[38:41], v[24:27], v[34:37]
	v_mfma_f32_16x16x32_bf16 v[34:37], v[38:41], v[20:23], v[34:37]
	s_nop 7
	v_max_f32_e32 v38, v34, v34
	v_mul_f32_e64 v34, |v34|, s89
	v_exp_f32_e32 v34, v34
	v_mul_f32_e64 v39, |v35|, s89
	v_exp_f32_e32 v39, v39
	v_min_f32_e32 v38, 0, v38
	v_add_f32_e32 v34, 1.0, v34
	v_add_f32_e32 v39, 1.0, v39
	v_log_f32_e32 v34, v34
	v_log_f32_e32 v39, v39
	v_mul_f32_e32 v41, 0x3f317217, v34
	v_fma_f32 v41, v34, s91, -v41
	v_fmac_f32_e32 v41, 0x3377d1cf, v34
	v_fmac_f32_e32 v41, 0x3f317217, v34
	v_mul_f32_e32 v42, 0x3f317217, v39
	v_max_f32_e32 v35, v35, v35
	v_mov_b32_e32 v34, v41
	v_sub_f32_e32 v34, v38, v34
	v_fma_f32 v38, v39, s91, -v42
	v_fmac_f32_e32 v38, 0x3377d1cf, v39
	v_fmac_f32_e32 v38, 0x3f317217, v39
	v_min_f32_e32 v35, 0, v35
	v_mul_f32_e64 v39, |v36|, s89
	v_exp_f32_e32 v39, v39
	v_sub_f32_e32 v35, v35, v38
	v_max_f32_e32 v36, v36, v36
	v_add_f32_e32 v38, 1.0, v39
	v_min_f32_e32 v36, 0, v36
	v_fma_f32 v34, v34, s93, 0
	v_log_f32_e32 v38, v38
	v_fmamk_f32 v35, v35, 0x3d800000, v34
	v_mul_f32_e32 v39, 0x3f317217, v38
	v_fma_f32 v39, v38, s91, -v39
	v_fmac_f32_e32 v39, 0x3377d1cf, v38
	v_fmac_f32_e32 v39, 0x3f317217, v38
	s_nop 1
	v_mov_b32_e32 v38, v39
	v_mul_f32_e64 v39, |v37|, s89
	v_exp_f32_e32 v39, v39
	v_sub_f32_e32 v36, v36, v38
	v_max_f32_e32 v37, v37, v37
	v_add_f32_e32 v38, 1.0, v39
	v_min_f32_e32 v37, 0, v37
	v_fmamk_f32 v36, v36, 0x3d800000, v35
	v_log_f32_e32 v38, v38
	s_waitcnt lgkmcnt(2)
	v_add_f32_e32 v40, 0, v33
	v_mul_f32_e32 v39, 0x3f317217, v38
	v_fma_f32 v39, v38, s91, -v39
	v_fmac_f32_e32 v39, 0x3377d1cf, v38
	v_fmac_f32_e32 v39, 0x3f317217, v38
	s_nop 1
	v_mov_b32_e32 v38, v39
	v_sub_f32_e32 v37, v37, v38
	v_fmamk_f32 v37, v37, 0x3d800000, v36
	v_mov_b32_e32 v241, v37
	v_mov_b32_e32 v242, v37
	s_nop 1
	v_permlane16_swap_b32_e32 v241, v242
	v_mov_b32_e32 v243, v242
	s_nop 1
	v_permlane32_swap_b32_e32 v242, v243
	v_cndmask_b32_e64 v38, v241, v242, s[96:97]
	v_cndmask_b32_e64 v38, v38, 0, s[8:9]
	v_add_f32_e32 v38, v38, v37
	v_mov_b32_e32 v244, v38
	v_mov_b32_e32 v245, v38
	s_nop 1
	v_permlane32_swap_b32_e32 v244, v245
	v_cndmask_b32_e64 v33, 0, v244, s[10:11]
	v_add_f32_e32 v33, v33, v38
	v_sub_f32_e32 v38, v33, v37
	v_mov_b32_e32 v246, v33
	v_mov_b32_e32 v247, v33
	s_nop 1
	v_permlane32_swap_b32_e32 v246, v247
	v_mov_b32_e32 v248, v247
	s_nop 1
	v_permlane16_swap_b32_e32 v247, v248
	v_mov_b32_e32 v41, v248
	v_add_f32_e32 v38, v40, v38
	v_add_f32_e32 v33, v34, v38
	v_add_f32_e32 v34, v35, v38
	v_add_u32_e32 v35, 0xa800, v98
	ds_write2_b32 v35, v33, v34 offset0:64 offset1:196
	v_add_f32_e32 v33, v36, v38
	v_add_f32_e32 v34, v37, v38
	v_add_u32_e32 v35, 0xac00, v98
	ds_write2_b32 v35, v33, v34 offset0:72 offset1:204
	v_mov_b32_e32 v33, 0
	v_mov_b32_e32 v34, 0
	v_mov_b32_e32 v35, 0
	v_mov_b32_e32 v36, 0
	v_mov_b32_e32 v37, 0
	v_mov_b32_e32 v38, 0
	v_mov_b32_e32 v39, 0
	s_and_saveexec_b64 s[36:37], s[6:7]
	s_cbranch_execz .LBB0_490
	ds_read_b128 v[32:35], v96 offset:2048
	ds_read_b128 v[36:39], v96 offset:2064
	s_waitcnt lgkmcnt(1)
	v_and_b32_sdwa v42, v33, v95 dst_sel:DWORD dst_unused:UNUSED_PAD src0_sel:WORD_1 src1_sel:DWORD
	v_and_b32_sdwa v43, v32, v95 dst_sel:DWORD dst_unused:UNUSED_PAD src0_sel:WORD_1 src1_sel:DWORD
	v_add3_u32 v44, v33, v42, s86
	v_add3_u32 v45, v32, v43, s86
	v_and_b32_e32 v43, 0xffff0000, v44
	v_and_b32_e32 v42, 0xffff0000, v45
	v_cvt_pk_bf16_f32 v204, v32, v33
	v_pk_add_f32 v[32:33], v[32:33], v[42:43] neg_lo:[0,1] neg_hi:[0,1]
	v_and_b32_sdwa v42, v35, v95 dst_sel:DWORD dst_unused:UNUSED_PAD src0_sel:WORD_1 src1_sel:DWORD
	v_and_b32_sdwa v43, v34, v95 dst_sel:DWORD dst_unused:UNUSED_PAD src0_sel:WORD_1 src1_sel:DWORD
	v_add3_u32 v46, v35, v42, s86
	v_add3_u32 v47, v34, v43, s86
	v_and_b32_e32 v43, 0xffff0000, v46
	v_and_b32_e32 v42, 0xffff0000, v47
	v_cvt_pk_bf16_f32 v205, v34, v35
	v_pk_add_f32 v[34:35], v[34:35], v[42:43] neg_lo:[0,1] neg_hi:[0,1]
	s_waitcnt lgkmcnt(0)
	v_and_b32_sdwa v42, v37, v95 dst_sel:DWORD dst_unused:UNUSED_PAD src0_sel:WORD_1 src1_sel:DWORD
	v_and_b32_sdwa v43, v36, v95 dst_sel:DWORD dst_unused:UNUSED_PAD src0_sel:WORD_1 src1_sel:DWORD
	v_add3_u32 v60, v37, v42, s86
	v_add3_u32 v61, v36, v43, s86
	v_and_b32_e32 v43, 0xffff0000, v60
	v_and_b32_e32 v42, 0xffff0000, v61
	v_cvt_pk_bf16_f32 v206, v36, v37
	v_pk_add_f32 v[36:37], v[36:37], v[42:43] neg_lo:[0,1] neg_hi:[0,1]
	v_and_b32_sdwa v42, v39, v95 dst_sel:DWORD dst_unused:UNUSED_PAD src0_sel:WORD_1 src1_sel:DWORD
	v_and_b32_sdwa v43, v38, v95 dst_sel:DWORD dst_unused:UNUSED_PAD src0_sel:WORD_1 src1_sel:DWORD
	v_add3_u32 v62, v39, v42, s86
	v_add3_u32 v63, v38, v43, s86
	v_and_b32_e32 v43, 0xffff0000, v62
	v_and_b32_e32 v42, 0xffff0000, v63
	v_cvt_pk_bf16_f32 v208, v38, v39
	v_pk_add_f32 v[38:39], v[38:39], v[42:43] neg_lo:[0,1] neg_hi:[0,1]
	s_nop 0
	v_cvt_pk_bf16_f32 v203, v38, v39
	v_cvt_pk_bf16_f32 v202, v36, v37
	v_cvt_pk_bf16_f32 v201, v34, v35
	v_cvt_pk_bf16_f32 v200, v32, v33
	v_mov_b32_e32 v32, v200
	v_mov_b32_e32 v33, v201
	v_mov_b32_e32 v34, v202
	v_mov_b32_e32 v35, v203
	v_mov_b32_e32 v36, v204
	v_mov_b32_e32 v37, v205
	v_mov_b32_e32 v38, v206
	v_mov_b32_e32 v39, v208
; #define LAS __attribute__((address_space(3)))
; __device__ __forceinline__ void phase_gla_pre(const Params& P, LAS unsigned char* lds, bool dry) {
;     ...
;             if (g < 2) { const f32x4 l0 = *(const LAS f32x4*)(Llr + (16 * tt + fr) * 16 + 8 * g), l1 = *(const LAS f32x4*)(Llr + (16 * tt + fr) * 16 + 8 * g + 4); split8(l0, l1, ahi, alo); }
;             f32x4 acc = (f32x4){bg, bg, bg, bg};
;             acc = __builtin_amdgcn_mfma_f32_16x16x32_bf16(alo, bhi, acc, 0, 0, 0); acc = __builtin_amdgcn_mfma_f32_16x16x32_bf16(ahi, blo, acc, 0, 0, 0); acc = __builtin_amdgcn_mfma_f32_16x16x32_bf16(ahi, bhi, acc, 0, 0, 0);
;             float pr[4];
; #pragma unroll
;             for (int r = 0; r < 4; ++r) { const float lg = acc[r]; const float ls = fminf(lg, 0.f) - __logf(1.0f + __expf(-fabsf(lg))); pr[r] = ls * (1.0f / 16.0f) + (r ? pr[r - 1] : 0.f); }
;             const float T = pr[3];
;             const float u1 = __shfl_up(T, 16), s1 = T + (g >= 1 ? u1 : 0.f);
;             const float u2 = __shfl_up(s1, 32), s2 = s1 + (g >= 2 ? u2 : 0.f);
;             const float base = run + (s2 - T); run += __shfl(s2, 48 + fr);
; #pragma unroll
;             for (int r = 0; r < 4; ++r) *(LAS float*)(Lb + (16 * tt + 4 * g + r) * BP + (16 * w + fr) * 4) = base + pr[r];
.LBB0_490:
	s_or_b64 exec, exec, s[36:37]
	v_mfma_f32_16x16x32_bf16 v[32:35], v[32:35], v[20:23], v[28:31]
	s_waitcnt lgkmcnt(2)
	v_add_f32_e32 v40, v40, v41
	v_mfma_f32_16x16x32_bf16 v[32:35], v[36:39], v[24:27], v[32:35]
	v_mfma_f32_16x16x32_bf16 v[32:35], v[36:39], v[20:23], v[32:35]
	s_nop 7
	v_max_f32_e32 v36, v32, v32
	v_mul_f32_e64 v32, |v32|, s89
	v_exp_f32_e32 v32, v32
	v_mul_f32_e64 v37, |v33|, s89
	v_exp_f32_e32 v37, v37
	v_min_f32_e32 v36, 0, v36
	v_add_f32_e32 v32, 1.0, v32
	v_add_f32_e32 v37, 1.0, v37
	v_log_f32_e32 v32, v32
	v_log_f32_e32 v37, v37
	v_mul_f32_e32 v39, 0x3f317217, v32
	v_fma_f32 v39, v32, s91, -v39
	v_fmac_f32_e32 v39, 0x3377d1cf, v32
	v_fmac_f32_e32 v39, 0x3f317217, v32
	v_mul_f32_e32 v42, 0x3f317217, v37
	v_max_f32_e32 v33, v33, v33
	v_mov_b32_e32 v32, v39
	v_sub_f32_e32 v32, v36, v32
	v_fma_f32 v36, v37, s91, -v42
	v_fmac_f32_e32 v36, 0x3377d1cf, v37
	v_fmac_f32_e32 v36, 0x3f317217, v37
	v_min_f32_e32 v33, 0, v33
	v_mul_f32_e64 v37, |v34|, s89
	v_exp_f32_e32 v37, v37
	v_sub_f32_e32 v33, v33, v36
	v_max_f32_e32 v34, v34, v34
	v_add_f32_e32 v36, 1.0, v37
	v_min_f32_e32 v34, 0, v34
	v_fma_f32 v32, v32, s93, 0
	v_log_f32_e32 v36, v36
	v_fmamk_f32 v33, v33, 0x3d800000, v32
	v_mov_b32_e32 v39, 0
	v_mul_f32_e32 v37, 0x3f317217, v36
	v_fma_f32 v37, v36, s91, -v37
	v_fmac_f32_e32 v37, 0x3377d1cf, v36
	v_fmac_f32_e32 v37, 0x3f317217, v36
	s_nop 1
	v_mov_b32_e32 v36, v37
	v_mul_f32_e64 v37, |v35|, s89
	v_exp_f32_e32 v37, v37
	v_sub_f32_e32 v34, v34, v36
	v_max_f32_e32 v35, v35, v35
	v_add_f32_e32 v36, 1.0, v37
	v_min_f32_e32 v35, 0, v35
	v_fmamk_f32 v34, v34, 0x3d800000, v33
	v_log_f32_e32 v36, v36
	v_mov_b32_e32 v38, 0
	v_mul_f32_e32 v37, 0x3f317217, v36
	v_fma_f32 v37, v36, s91, -v37
	v_fmac_f32_e32 v37, 0x3377d1cf, v36
	v_fmac_f32_e32 v37, 0x3f317217, v36
	s_nop 1
	v_mov_b32_e32 v36, v37
	v_sub_f32_e32 v35, v35, v36
	v_fmamk_f32 v35, v35, 0x3d800000, v34
	v_mov_b32_e32 v241, v35
	v_mov_b32_e32 v242, v35
	s_nop 1
	v_permlane16_swap_b32_e32 v241, v242
	v_mov_b32_e32 v243, v242
	s_nop 1
	v_permlane32_swap_b32_e32 v242, v243
	v_cndmask_b32_e64 v36, v241, v242, s[96:97]
	v_cndmask_b32_e64 v36, v36, 0, s[8:9]
	v_add_f32_e32 v36, v36, v35
	v_mov_b32_e32 v244, v36
	v_mov_b32_e32 v245, v36
	s_nop 1
	v_permlane32_swap_b32_e32 v244, v245
	v_cndmask_b32_e64 v37, 0, v244, s[10:11]
	v_add_f32_e32 v36, v37, v36
	v_sub_f32_e32 v37, v36, v35
	v_mov_b32_e32 v246, v36
	v_mov_b32_e32 v247, v36
	s_nop 1
	v_permlane32_swap_b32_e32 v246, v247
	v_mov_b32_e32 v248, v247
	s_nop 1
	v_permlane16_swap_b32_e32 v247, v248
	v_mov_b32_e32 v41, v248
	v_add_f32_e32 v37, v40, v37
	v_add_f32_e32 v32, v32, v37
	v_add_f32_e32 v33, v33, v37
	v_add_u32_e32 v36, 0xca00, v98
	ds_write2_b32 v36, v32, v33 offset1:132
	v_add_f32_e32 v32, v34, v37
	v_add_f32_e32 v33, v35, v37
	v_add_u32_e32 v34, 0xce00, v98
	ds_write2_b32 v34, v32, v33 offset0:8 offset1:140
	v_mov_b32_e32 v32, 0
	v_mov_b32_e32 v33, 0
	v_mov_b32_e32 v34, 0
	v_mov_b32_e32 v35, 0
	v_mov_b32_e32 v36, 0
	v_mov_b32_e32 v37, 0
	s_and_saveexec_b64 s[36:37], s[6:7]
	s_cbranch_execz .LBB0_492
	ds_read_b128 v[32:35], v96 offset:3072
	ds_read_b128 v[36:39], v96 offset:3088
	s_waitcnt lgkmcnt(1)
	v_and_b32_sdwa v42, v33, v95 dst_sel:DWORD dst_unused:UNUSED_PAD src0_sel:WORD_1 src1_sel:DWORD
	v_and_b32_sdwa v43, v32, v95 dst_sel:DWORD dst_unused:UNUSED_PAD src0_sel:WORD_1 src1_sel:DWORD
	v_add3_u32 v44, v33, v42, s86
	v_add3_u32 v45, v32, v43, s86
	v_and_b32_e32 v43, 0xffff0000, v44
	v_and_b32_e32 v42, 0xffff0000, v45
	v_cvt_pk_bf16_f32 v214, v32, v33
	v_pk_add_f32 v[32:33], v[32:33], v[42:43] neg_lo:[0,1] neg_hi:[0,1]
	v_and_b32_sdwa v42, v35, v95 dst_sel:DWORD dst_unused:UNUSED_PAD src0_sel:WORD_1 src1_sel:DWORD
	v_and_b32_sdwa v43, v34, v95 dst_sel:DWORD dst_unused:UNUSED_PAD src0_sel:WORD_1 src1_sel:DWORD
	v_add3_u32 v46, v35, v42, s86
	v_add3_u32 v47, v34, v43, s86
	v_and_b32_e32 v43, 0xffff0000, v46
	v_and_b32_e32 v42, 0xffff0000, v47
	v_cvt_pk_bf16_f32 v216, v34, v35
	v_pk_add_f32 v[34:35], v[34:35], v[42:43] neg_lo:[0,1] neg_hi:[0,1]
	s_waitcnt lgkmcnt(0)
	v_and_b32_sdwa v42, v37, v95 dst_sel:DWORD dst_unused:UNUSED_PAD src0_sel:WORD_1 src1_sel:DWORD
	v_and_b32_sdwa v43, v36, v95 dst_sel:DWORD dst_unused:UNUSED_PAD src0_sel:WORD_1 src1_sel:DWORD
	v_add3_u32 v60, v37, v42, s86
	v_add3_u32 v61, v36, v43, s86
	v_and_b32_e32 v43, 0xffff0000, v60
	v_and_b32_e32 v42, 0xffff0000, v61
	v_cvt_pk_bf16_f32 v217, v36, v37
	v_pk_add_f32 v[36:37], v[36:37], v[42:43] neg_lo:[0,1] neg_hi:[0,1]
	v_and_b32_sdwa v42, v39, v95 dst_sel:DWORD dst_unused:UNUSED_PAD src0_sel:WORD_1 src1_sel:DWORD
	v_and_b32_sdwa v43, v38, v95 dst_sel:DWORD dst_unused:UNUSED_PAD src0_sel:WORD_1 src1_sel:DWORD
	v_add3_u32 v62, v39, v42, s86
	v_add3_u32 v63, v38, v43, s86
	v_and_b32_e32 v43, 0xffff0000, v62
	v_and_b32_e32 v42, 0xffff0000, v63
	v_cvt_pk_bf16_f32 v218, v38, v39
	v_pk_add_f32 v[38:39], v[38:39], v[42:43] neg_lo:[0,1] neg_hi:[0,1]
	s_nop 0
	v_cvt_pk_bf16_f32 v213, v38, v39
	v_cvt_pk_bf16_f32 v212, v36, v37
	v_cvt_pk_bf16_f32 v210, v34, v35
	v_cvt_pk_bf16_f32 v209, v32, v33
	v_mov_b32_e32 v32, v209
	v_mov_b32_e32 v33, v210
	v_mov_b32_e32 v34, v212
	v_mov_b32_e32 v35, v213
	v_mov_b32_e32 v36, v214
	v_mov_b32_e32 v37, v216
	v_mov_b32_e32 v38, v217
	v_mov_b32_e32 v39, v218
; #define LAS __attribute__((address_space(3)))
; __device__ __forceinline__ float bflo(unsigned w) { return __uint_as_float(w << 16); }
; __device__ __forceinline__ float bfhi(unsigned w) { return __uint_as_float(w & 0xffff0000u); }
; __device__ __forceinline__ void phase_gla_pre(const Params& P, LAS unsigned char* lds, bool dry) {
;     ...
;             acc = __builtin_amdgcn_mfma_f32_16x16x32_bf16(alo, bhi, acc, 0, 0, 0); acc = __builtin_amdgcn_mfma_f32_16x16x32_bf16(ahi, blo, acc, 0, 0, 0); acc = __builtin_amdgcn_mfma_f32_16x16x32_bf16(ahi, bhi, acc, 0, 0, 0);
;             float pr[4];
; #pragma unroll
;             for (int r = 0; r < 4; ++r) { const float lg = acc[r]; const float ls = fminf(lg, 0.f) - __logf(1.0f + __expf(-fabsf(lg))); pr[r] = ls * (1.0f / 16.0f) + (r ? pr[r - 1] : 0.f); }
;             const float T = pr[3];
;             const float u1 = __shfl_up(T, 16), s1 = T + (g >= 1 ? u1 : 0.f);
;             const float u2 = __shfl_up(s1, 32), s2 = s1 + (g >= 2 ? u2 : 0.f);
;             const float base = run + (s2 - T); run += __shfl(s2, 48 + fr);
; #pragma unroll
;             for (int r = 0; r < 4; ++r) *(LAS float*)(Lb + (16 * tt + 4 * g + r) * BP + (16 * w + fr) * 4) = base + pr[r];
;         }
;         __syncthreads();
;         {
;             f32x4 bb[4], bm[4], bl[4];
; #pragma unroll
;             for (int i = 0; i < 4; ++i) { bb[i] = *(const LAS f32x4*)(Lb + te * BP + (16 * kc + 4 * i) * 4); bm[i] = *(const LAS f32x4*)(Lb + 31 * BP + (16 * kc + 4 * i) * 4); bl[i] = *(const LAS f32x4*)(Lb + 63 * BP + (16 * kc + 4 * i) * 4); }
;             unsigned oqi[8], oki[8], oqd[8], oks[8];
; #pragma unroll
;             for (int e2 = 0; e2 < 8; ++e2) {
;                 const unsigned qw = e2 < 4 ? rq[0][e2] : rq[1][e2 - 4], kw = e2 < 4 ? rk[0][e2] : rk[1][e2 - 4];
;                 float vqi[2], vki[2], vqd[2], vks[2];
; #pragma unroll
;                 for (int hh = 0; hh < 2; ++hh) {
;                     const int e = 2 * e2 + hh; const float bv = bb[e >> 2][e & 3], bmv = bm[e >> 2][e & 3], blv = bl[e >> 2][e & 3];
;                     const float qv = hh ? bfhi(qw) : bflo(qw), kv = hh ? bfhi(kw) : bflo(kw);
;                     const float e1 = __expf(bv - bmv);
;                     vqi[hh] = qv * e1; vki[hh] = kv * __builtin_amdgcn_rcpf(e1); vqd[hh] = qv * __expf(bv); vks[hh] = kv * __expf(blv - bv);
.LBB0_492:
	s_or_b64 exec, exec, s[36:37]
	v_mfma_f32_16x16x32_bf16 v[28:31], v[32:35], v[20:23], v[28:31]
	v_and_b32_e32 v111, 0xffff0000, v5
	v_and_b32_e32 v110, 0xffff0000, v4
	v_and_b32_e32 v117, 0xffff0000, v13
	v_mfma_f32_16x16x32_bf16 v[24:27], v[36:39], v[24:27], v[28:31]
	v_and_b32_e32 v116, 0xffff0000, v12
	v_and_b32_e32 v121, 0xffff0000, v7
	v_and_b32_e32 v120, 0xffff0000, v6
	v_mfma_f32_16x16x32_bf16 v[20:23], v[36:39], v[20:23], v[24:27]
	v_and_b32_e32 v127, 0xffff0000, v17
	v_and_b32_e32 v126, 0xffff0000, v16
	v_lshlrev_b32_e32 v125, 16, v17
	v_lshlrev_b32_e32 v124, 16, v16
	v_lshlrev_b32_e32 v133, 16, v11
	s_nop 2
	v_max_f32_e32 v24, v20, v20
	v_mul_f32_e64 v20, |v20|, s89
	v_exp_f32_e32 v20, v20
	v_mul_f32_e64 v25, |v21|, s89
	v_exp_f32_e32 v25, v25
	v_min_f32_e32 v24, 0, v24
	v_add_f32_e32 v20, 1.0, v20
	v_add_f32_e32 v25, 1.0, v25
	v_log_f32_e32 v20, v20
	v_log_f32_e32 v25, v25
	v_mul_f32_e32 v27, 0x3f317217, v20
	v_fma_f32 v27, v20, s91, -v27
	v_fmac_f32_e32 v27, 0x3377d1cf, v20
	v_fmac_f32_e32 v27, 0x3f317217, v20
	v_mul_f32_e32 v28, 0x3f317217, v25
	v_max_f32_e32 v21, v21, v21
	v_mov_b32_e32 v20, v27
	v_sub_f32_e32 v20, v24, v20
	v_fma_f32 v24, v25, s91, -v28
	v_fmac_f32_e32 v24, 0x3377d1cf, v25
	v_fmac_f32_e32 v24, 0x3f317217, v25
	v_min_f32_e32 v21, 0, v21
	v_mul_f32_e64 v25, |v22|, s89
	v_exp_f32_e32 v25, v25
	v_sub_f32_e32 v21, v21, v24
	v_max_f32_e32 v22, v22, v22
	v_add_f32_e32 v24, 1.0, v25
	v_min_f32_e32 v22, 0, v22
	v_fma_f32 v20, v20, s93, 0
	v_log_f32_e32 v24, v24
	v_fmamk_f32 v21, v21, 0x3d800000, v20
	v_lshlrev_b32_e32 v132, 16, v10
	v_mul_f32_e32 v25, 0x3f317217, v24
	v_fma_f32 v25, v24, s91, -v25
	v_fmac_f32_e32 v25, 0x3377d1cf, v24
	v_fmac_f32_e32 v25, 0x3f317217, v24
	v_and_b32_e32 v135, 0xffff0000, v11
	v_and_b32_e32 v134, 0xffff0000, v10
	v_mov_b32_e32 v24, v25
	v_mul_f32_e64 v25, |v23|, s89
	v_exp_f32_e32 v25, v25
	v_sub_f32_e32 v22, v22, v24
	v_max_f32_e32 v23, v23, v23
	v_add_f32_e32 v24, 1.0, v25
	v_min_f32_e32 v23, 0, v23
	v_fmamk_f32 v22, v22, 0x3d800000, v21
	v_log_f32_e32 v24, v24
	s_waitcnt lgkmcnt(2)
	v_add_f32_e32 v26, v40, v41
	s_and_b32 s74, s1, 0xfc0
	s_ashr_i32 s83, s82, 31
	v_mul_f32_e32 v25, 0x3f317217, v24
	v_fma_f32 v25, v24, s91, -v25
	v_fmac_f32_e32 v25, 0x3377d1cf, v24
	v_fmac_f32_e32 v25, 0x3f317217, v24
	s_nop 1
	v_mov_b32_e32 v24, v25
	v_sub_f32_e32 v23, v23, v24
	v_fmamk_f32 v23, v23, 0x3d800000, v22
	v_mov_b32_e32 v241, v23
	v_mov_b32_e32 v242, v23
	s_nop 1
	v_permlane16_swap_b32_e32 v241, v242
	v_mov_b32_e32 v243, v242
	s_nop 1
	v_permlane32_swap_b32_e32 v242, v243
	v_cndmask_b32_e64 v24, v241, v242, s[96:97]
	s_lshl_b64 s[36:37], s[82:83], 20
	v_cndmask_b32_e64 v24, v24, 0, s[8:9]
	v_add_f32_e32 v24, v24, v23
	v_mov_b32_e32 v244, v24
	v_mov_b32_e32 v245, v24
	s_nop 1
	v_permlane32_swap_b32_e32 v244, v245
	v_cndmask_b32_e64 v25, 0, v244, s[10:11]
	v_add_f32_e32 v24, v25, v24
	v_sub_f32_e32 v24, v24, v23
	v_add_f32_e32 v24, v26, v24
	v_add_f32_e32 v20, v20, v24
	v_add_f32_e32 v21, v21, v24
	v_add_u32_e32 v25, 0xea00, v98
	ds_write2_b32 v25, v20, v21 offset0:64 offset1:196
	v_add_f32_e32 v20, v22, v24
	v_add_f32_e32 v21, v23, v24
	v_add_u32_e32 v22, 0xee00, v98
	ds_write2_b32 v22, v20, v21 offset0:72 offset1:204
	v_add_u32_e32 v22, s94, v87
	s_waitcnt lgkmcnt(0)
	s_barrier
	v_add_u32_e32 v20, v86, v87
	v_add_u32_e32 v21, 0, v87
	ds_read_b128 v[32:35], v22
	ds_read_b128 v[24:27], v89
	ds_read_b128 v[60:63], v21 offset:51184
	ds_read_b128 v[64:67], v20 offset:34816
	ds_read_b128 v[74:77], v20 offset:34832
	ds_read_b128 v[44:47], v20 offset:34848
	ds_read_b128 v[36:39], v20 offset:34864
	ds_read_b128 v[100:103], v21 offset:51200
	s_waitcnt lgkmcnt(4)
	v_sub_f32_e32 v61, v65, v61
	v_mul_f32_e32 v61, 0x3fb8aa3b, v61
	v_sub_f32_e32 v63, v67, v63
	v_exp_f32_e32 v72, v61
	v_sub_f32_e32 v61, v32, v64
	v_mul_f32_e32 v63, 0x3fb8aa3b, v63
	v_mul_f32_e32 v61, 0x3fb8aa3b, v61
	v_exp_f32_e32 v73, v63
	v_exp_f32_e32 v78, v61
	v_mul_f32_e32 v61, 0x3fb8aa3b, v65
	v_sub_f32_e32 v20, v64, v60
	v_exp_f32_e32 v108, v61
	v_sub_f32_e32 v61, v66, v62
	v_mul_f32_e32 v20, 0x3fb8aa3b, v20
	v_mul_f32_e32 v69, 0x3fb8aa3b, v64
	v_mul_f32_e32 v61, 0x3fb8aa3b, v61
	v_sub_f32_e32 v62, v33, v65
	v_mul_f32_e32 v65, 0x3fb8aa3b, v66
	v_sub_f32_e32 v63, v34, v66
	v_exp_f32_e32 v60, v20
	v_exp_f32_e32 v70, v69
	v_rcp_f32_e32 v64, v72
	v_exp_f32_e32 v61, v61
	v_exp_f32_e32 v71, v65
	v_mul_f32_e32 v63, 0x3fb8aa3b, v63
	v_rcp_f32_e32 v65, v73
	v_exp_f32_e32 v79, v63
	v_mul_f32_e32 v63, 0x3fb8aa3b, v67
	v_exp_f32_e32 v109, v63
	v_sub_f32_e32 v63, v35, v67
	v_lshlrev_b32_e32 v67, 16, v5
	v_lshlrev_b32_e32 v66, 16, v4
	v_pk_mul_f32 v[112:113], v[60:61], v[66:67]
	v_pk_mul_f32 v[114:115], v[72:73], v[110:111]
	v_pk_mul_f32 v[72:73], v[64:65], v[116:117]
	v_pk_mul_f32 v[64:65], v[70:71], v[66:67]
	s_waitcnt lgkmcnt(0)
; __device__ __forceinline__ float bflo(unsigned w) { return __uint_as_float(w << 16); }
; __device__ __forceinline__ float bfhi(unsigned w) { return __uint_as_float(w & 0xffff0000u); }
; __device__ __forceinline__ unsigned pk2(float lo, float hi) { return f2bf(lo) | (f2bf(hi) << 16); }
; __device__ __forceinline__ void phase_gla_pre(const Params& P, LAS unsigned char* lds, bool dry) {
;     ...
;             for (int e2 = 0; e2 < 8; ++e2) {
;                 const unsigned qw = e2 < 4 ? rq[0][e2] : rq[1][e2 - 4], kw = e2 < 4 ? rk[0][e2] : rk[1][e2 - 4];
;                 float vqi[2], vki[2], vqd[2], vks[2];
; #pragma unroll
;                 for (int hh = 0; hh < 2; ++hh) {
;                     const int e = 2 * e2 + hh; const float bv = bb[e >> 2][e & 3], bmv = bm[e >> 2][e & 3], blv = bl[e >> 2][e & 3];
;                     const float qv = hh ? bfhi(qw) : bflo(qw), kv = hh ? bfhi(kw) : bflo(kw);
;                     const float e1 = __expf(bv - bmv);
;                     vqi[hh] = qv * e1; vki[hh] = kv * __builtin_amdgcn_rcpf(e1); vqd[hh] = qv * __expf(bv); vks[hh] = kv * __expf(blv - bv);
;                 }
;                 oqi[e2] = pk2(vqi[0], vqi[1]); oki[e2] = pk2(vki[0], vki[1]); oqd[e2] = pk2(vqd[0], vqd[1]); oks[e2] = pk2(vks[0], vks[1]);
	v_sub_f32_e32 v66, v74, v100
	v_mul_f32_e32 v66, 0x3fb8aa3b, v66
	v_mul_f32_e32 v71, 0x3fb8aa3b, v74
	v_exp_f32_e32 v70, v66
	v_pk_mul_f32 v[66:67], v[108:109], v[110:111]
	v_exp_f32_e32 v108, v71
	v_sub_f32_e32 v71, v75, v101
	v_mul_f32_e32 v71, 0x3fb8aa3b, v71
	v_mul_f32_e32 v62, 0x3fb8aa3b, v62
	v_mul_f32_e32 v63, 0x3fb8aa3b, v63
	v_exp_f32_e32 v100, v71
	v_sub_f32_e32 v71, v24, v74
	v_exp_f32_e32 v62, v62
	v_exp_f32_e32 v63, v63
	v_mul_f32_e32 v71, 0x3fb8aa3b, v71
	v_exp_f32_e32 v74, v71
	v_mul_f32_e32 v71, 0x3fb8aa3b, v75
	v_sub_f32_e32 v75, v25, v75
	v_mul_f32_e32 v75, 0x3fb8aa3b, v75
	v_exp_f32_e32 v118, v75
	v_mul_f32_e32 v75, 0x3fb8aa3b, v76
	v_pk_mul_f32 v[62:63], v[62:63], v[116:117]
	v_exp_f32_e32 v116, v71
	v_sub_f32_e32 v71, v76, v102
	v_exp_f32_e32 v109, v75
	v_sub_f32_e32 v75, v77, v103
	v_mul_f32_e32 v71, 0x3fb8aa3b, v71
	v_mul_f32_e32 v75, 0x3fb8aa3b, v75
	v_rcp_f32_e32 v68, v60
	v_rcp_f32_e32 v69, v61
	v_exp_f32_e32 v71, v71
	v_exp_f32_e32 v101, v75
	v_sub_f32_e32 v75, v26, v76
	v_mul_f32_e32 v76, 0x3fb8aa3b, v77
	v_exp_f32_e32 v117, v76
	v_sub_f32_e32 v76, v27, v77
	v_mul_f32_e32 v76, 0x3fb8aa3b, v76
	v_lshlrev_b32_e32 v61, 16, v13
	v_lshlrev_b32_e32 v60, 16, v12
	v_exp_f32_e32 v119, v76
	v_lshlrev_b32_e32 v77, 16, v7
	v_lshlrev_b32_e32 v76, 16, v6
	v_pk_mul_f32 v[68:69], v[68:69], v[60:61]
	v_pk_mul_f32 v[60:61], v[78:79], v[60:61]
	v_rcp_f32_e32 v78, v70
	v_rcp_f32_e32 v110, v100
	v_rcp_f32_e32 v79, v71
	v_rcp_f32_e32 v111, v101
	v_pk_mul_f32 v[70:71], v[70:71], v[76:77]
	v_pk_mul_f32 v[100:101], v[100:101], v[120:121]
	v_cvt_pk_bf16_f32 v224, v112, v114
	v_cvt_pk_bf16_f32 v222, v113, v115
	v_cvt_pk_bf16_f32 v221, v70, v100
	v_cvt_pk_bf16_f32 v220, v71, v101
	ds_read_b128 v[104:107], v21 offset:51216
	ds_read_b128 v[40:43], v21 offset:51232
	ds_read_b128 v[28:31], v90
	ds_read_b128 v[20:23], v91
	v_mov_b32_e32 v103, v220
	v_mov_b32_e32 v102, v221
	v_lshlrev_b32_e32 v71, 16, v15
	v_lshlrev_b32_e32 v70, 16, v14
	v_mul_f32_e32 v75, 0x3fb8aa3b, v75
	v_mov_b32_e32 v101, v222
	v_mov_b32_e32 v100, v224
	v_pk_mul_f32 v[114:115], v[78:79], v[70:71]
	s_waitcnt lgkmcnt(3)
	v_sub_f32_e32 v78, v44, v104
	v_sub_f32_e32 v105, v45, v105
	v_exp_f32_e32 v75, v75
	v_mul_f32_e32 v78, 0x3fb8aa3b, v78
	v_mul_f32_e32 v105, 0x3fb8aa3b, v105
	v_exp_f32_e32 v104, v78
	v_pk_mul_f32 v[78:79], v[116:117], v[120:121]
	v_exp_f32_e32 v116, v105
	v_mul_f32_e32 v105, 0x3fb8aa3b, v45
	s_waitcnt lgkmcnt(1)
	v_sub_f32_e32 v45, v29, v45
	v_mul_f32_e32 v45, 0x3fb8aa3b, v45
	v_and_b32_e32 v113, 0xffff0000, v15
	v_and_b32_e32 v112, 0xffff0000, v14
	v_exp_f32_e32 v120, v105
	v_sub_f32_e32 v105, v46, v106
	v_exp_f32_e32 v106, v45
	v_mul_f32_e32 v45, 0x3fb8aa3b, v46
	v_pk_mul_f32 v[110:111], v[110:111], v[112:113]
	v_pk_mul_f32 v[70:71], v[74:75], v[70:71]
	v_pk_mul_f32 v[74:75], v[118:119], v[112:113]
	v_exp_f32_e32 v113, v45
	v_sub_f32_e32 v45, v47, v107
	v_mul_f32_e32 v45, 0x3fb8aa3b, v45
	v_exp_f32_e32 v117, v45
	v_sub_f32_e32 v45, v30, v46
	v_mul_f32_e32 v46, 0x3fb8aa3b, v47
	v_exp_f32_e32 v121, v46
	v_sub_f32_e32 v46, v31, v47
	v_pk_mul_f32 v[76:77], v[108:109], v[76:77]
	v_mul_f32_e32 v109, 0x3fb8aa3b, v44
	v_mul_f32_e32 v105, 0x3fb8aa3b, v105
	v_mul_f32_e32 v46, 0x3fb8aa3b, v46
	v_exp_f32_e32 v112, v109
	v_exp_f32_e32 v105, v105
	v_exp_f32_e32 v107, v46
	v_rcp_f32_e32 v118, v116
	v_rcp_f32_e32 v119, v117
	v_sub_f32_e32 v44, v28, v44
	v_lshlrev_b32_e32 v47, 16, v9
	v_lshlrev_b32_e32 v46, 16, v8
	v_rcp_f32_e32 v108, v104
	v_mul_f32_e32 v44, 0x3fb8aa3b, v44
	v_rcp_f32_e32 v109, v105
	v_mul_f32_e32 v45, 0x3fb8aa3b, v45
	v_pk_mul_f32 v[104:105], v[104:105], v[46:47]
	v_pk_mul_f32 v[112:113], v[112:113], v[46:47]
	v_sub_f32_e32 v40, v36, v40
	v_pk_mul_f32 v[46:47], v[106:107], v[126:127]
	v_mul_f32_e32 v107, 0x3fb8aa3b, v36
	s_waitcnt lgkmcnt(0)
; #define LAS __attribute__((address_space(3)))
; __device__ __forceinline__ unsigned pk2(float lo, float hi) { return f2bf(lo) | (f2bf(hi) << 16); }
; __device__ __forceinline__ void phase_gla_pre(const Params& P, LAS unsigned char* lds, bool dry) {
;     ...
;                     const float e1 = __expf(bv - bmv);
;                     vqi[hh] = qv * e1; vki[hh] = kv * __builtin_amdgcn_rcpf(e1); vqd[hh] = qv * __expf(bv); vks[hh] = kv * __expf(blv - bv);
;                 }
;                 oqi[e2] = pk2(vqi[0], vqi[1]); oki[e2] = pk2(vki[0], vki[1]); oqd[e2] = pk2(vqd[0], vqd[1]); oks[e2] = pk2(vks[0], vks[1]);
;             }
;             *(LAS u32x4*)(Lqi + te * QP + 32 * kc) = (u32x4){oqi[0], oqi[1], oqi[2], oqi[3]}; *(LAS u32x4*)(Lqi + te * QP + 32 * kc + 16) = (u32x4){oqi[4], oqi[5], oqi[6], oqi[7]};
;             *(LAS u32x4*)(Lki + te * QP + 32 * kc) = (u32x4){oki[0], oki[1], oki[2], oki[3]}; *(LAS u32x4*)(Lki + te * QP + 32 * kc + 16) = (u32x4){oki[4], oki[5], oki[6], oki[7]};
;             if (!dry) {
;                 bf16_t* p_ = PJ + ((size_t)bh * SEQ + c * 64 + te) * 128 + 16 * kc;
;                 *(u32x4*)(p_ + T_Q) = (u32x4){oqd[0], oqd[1], oqd[2], oqd[3]}; *(u32x4*)(p_ + T_Q + 8) = (u32x4){oqd[4], oqd[5], oqd[6], oqd[7]};
;                 *(u32x4*)(p_ + T_K) = (u32x4){oks[0], oks[1], oks[2], oks[3]}; *(u32x4*)(p_ + T_K + 8) = (u32x4){oks[4], oks[5], oks[6], oks[7]};
;                 if (te == 63) {
; #pragma unroll
;                     for (int i = 0; i < 4; ++i) *(f32x4*)(DEC + (size_t)item * 128 + 16 * kc + 4 * i) = (f32x4){__expf(bl[i][0]), __expf(bl[i][1]), __expf(bl[i][2]), __expf(bl[i][3])};
;                 }
	v_sub_f32_e32 v36, v20, v36
	v_exp_f32_e32 v44, v44
	v_exp_f32_e32 v45, v45
	v_mul_f32_e32 v36, 0x3fb8aa3b, v36
	v_pk_mul_f32 v[118:119], v[118:119], v[126:127]
	v_exp_f32_e32 v126, v36
	v_mul_f32_e32 v36, 0x3fb8aa3b, v37
	v_sub_f32_e32 v41, v37, v41
	v_exp_f32_e32 v130, v36
	v_sub_f32_e32 v36, v38, v42
	v_mul_f32_e32 v41, 0x3fb8aa3b, v41
	v_mul_f32_e32 v36, 0x3fb8aa3b, v36
	v_pk_mul_f32 v[108:109], v[108:109], v[124:125]
	v_pk_mul_f32 v[44:45], v[44:45], v[124:125]
	v_exp_f32_e32 v124, v41
	v_exp_f32_e32 v41, v36
	v_sub_f32_e32 v36, v21, v37
	v_mul_f32_e32 v36, 0x3fb8aa3b, v36
	v_and_b32_e32 v123, 0xffff0000, v9
	v_and_b32_e32 v122, 0xffff0000, v8
	v_exp_f32_e32 v42, v36
	v_mul_f32_e32 v36, 0x3fb8aa3b, v38
	v_pk_mul_f32 v[116:117], v[116:117], v[122:123]
	v_pk_mul_f32 v[120:121], v[120:121], v[122:123]
	v_exp_f32_e32 v123, v36
	v_sub_f32_e32 v36, v39, v43
	v_mul_f32_e32 v36, 0x3fb8aa3b, v36
	v_mul_f32_e32 v40, 0x3fb8aa3b, v40
	v_exp_f32_e32 v125, v36
	v_sub_f32_e32 v36, v22, v38
	v_exp_f32_e32 v40, v40
	v_mul_f32_e32 v36, 0x3fb8aa3b, v36
	v_exp_f32_e32 v127, v36
	v_mul_f32_e32 v36, 0x3fb8aa3b, v39
	v_exp_f32_e32 v131, v36
	v_sub_f32_e32 v36, v23, v39
	v_mul_f32_e32 v36, 0x3fb8aa3b, v36
	v_rcp_f32_e32 v128, v124
	v_rcp_f32_e32 v129, v125
	v_exp_f32_e32 v43, v36
	v_pk_mul_f32 v[36:37], v[40:41], v[132:133]
	v_pk_mul_f32 v[38:39], v[124:125], v[134:135]
	v_rcp_f32_e32 v106, v40
	v_exp_f32_e32 v122, v107
	v_rcp_f32_e32 v107, v41
	v_cvt_pk_bf16_f32 v228, v104, v116
	v_cvt_pk_bf16_f32 v227, v105, v117
	v_cvt_pk_bf16_f32 v226, v36, v38
	v_cvt_pk_bf16_f32 v225, v37, v39
	v_mov_b32_e32 v39, v225
	v_mov_b32_e32 v38, v226
	v_mov_b32_e32 v37, v227
	v_mov_b32_e32 v36, v228
	ds_write_b128 v92, v[100:103]
	ds_write_b128 v92, v[36:39] offset:16
	v_cvt_pk_bf16_f32 v230, v68, v72
	v_cvt_pk_bf16_f32 v229, v69, v73
	v_lshlrev_b32_e32 v41, 16, v19
	v_lshlrev_b32_e32 v40, 16, v18
	v_cvt_pk_bf16_f32 v39, v115, v111
	v_cvt_pk_bf16_f32 v38, v114, v110
	v_mov_b32_e32 v37, v229
	v_mov_b32_e32 v36, v230
	v_and_b32_e32 v105, 0xffff0000, v19
	v_and_b32_e32 v104, 0xffff0000, v18
	v_pk_mul_f32 v[106:107], v[106:107], v[40:41]
	ds_write_b128 v92, v[36:39] offset:17408
	v_pk_mul_f32 v[116:117], v[128:129], v[104:105]
	s_nop 0
	v_cvt_pk_bf16_f32 v39, v107, v117
	v_cvt_pk_bf16_f32 v38, v106, v116
	v_cvt_pk_bf16_f32 v37, v109, v119
	v_cvt_pk_bf16_f32 v36, v108, v118
	ds_write_b128 v92, v[36:39] offset:17424
	v_lshl_add_u64 v[36:37], s[74:75], 0, v[48:49]
	v_lshlrev_b64 v[36:37], 8, v[36:37]
	v_lshl_add_u64 v[38:39], v[52:53], 0, s[36:37]
	v_lshl_add_u64 v[68:69], v[38:39], 0, v[36:37]
	v_cvt_pk_bf16_f32 v232, v64, v66
	v_cvt_pk_bf16_f32 v233, v65, v67
	s_brev_b32 s36, 16
	v_cvt_pk_bf16_f32 v39, v77, v79
	v_mov_b32_e32 v36, v232
	v_add_co_u32_e32 v64, vcc, s36, v68
	v_cvt_pk_bf16_f32 v38, v76, v78
	v_mov_b32_e32 v37, v233
	v_addc_co_u32_e32 v65, vcc, 0, v69, vcc
	v_pk_mul_f32 v[122:123], v[122:123], v[132:133]
	global_store_dwordx4 v[64:65], v[36:39], off
	v_pk_mul_f32 v[124:125], v[130:131], v[134:135]
	s_nop 0
	v_cvt_pk_bf16_f32 v39, v123, v125
	v_cvt_pk_bf16_f32 v38, v122, v124
	v_cvt_pk_bf16_f32 v37, v113, v121
	v_cvt_pk_bf16_f32 v36, v112, v120
	global_store_dwordx4 v[64:65], v[36:39], off offset:16
	s_nop 1
	s_nop 0
	v_cvt_pk_bf16_f32 v234, v60, v62
	v_cvt_pk_bf16_f32 v235, v61, v63
	v_cvt_pk_bf16_f32 v39, v71, v75
	v_mov_b32_e32 v36, v234
	v_add_co_u32_e32 v60, vcc, s95, v68
	v_pk_mul_f32 v[42:43], v[42:43], v[104:105]
	v_cvt_pk_bf16_f32 v38, v70, v74
	v_mov_b32_e32 v37, v235
	v_addc_co_u32_e32 v61, vcc, 0, v69, vcc
	v_pk_mul_f32 v[40:41], v[126:127], v[40:41]
	global_store_dwordx4 v[60:61], v[36:39], off
	s_nop 1
	v_cvt_pk_bf16_f32 v240, v44, v46
	v_cvt_pk_bf16_f32 v239, v45, v47
	v_cvt_pk_bf16_f32 v238, v40, v42
	v_cvt_pk_bf16_f32 v237, v41, v43
	v_mov_b32_e32 v39, v237
	v_mov_b32_e32 v38, v238
	v_mov_b32_e32 v37, v239
	v_mov_b32_e32 v36, v240
	global_store_dwordx4 v[60:61], v[36:39], off offset:16
	s_and_saveexec_b64 s[36:37], s[12:13]
	s_cbranch_execz .LBB0_494
	v_mul_f32_e32 v32, 0x3fb8aa3b, v32
	v_mul_f32_e32 v33, 0x3fb8aa3b, v33
	v_mul_f32_e32 v34, 0x3fb8aa3b, v34
	v_mul_f32_e32 v35, 0x3fb8aa3b, v35
	v_exp_f32_e32 v32, v32
	v_exp_f32_e32 v33, v33
	v_exp_f32_e32 v34, v34
	v_exp_f32_e32 v35, v35
	v_mul_f32_e32 v24, 0x3fb8aa3b, v24
	v_mul_f32_e32 v25, 0x3fb8aa3b, v25
	v_mul_f32_e32 v26, 0x3fb8aa3b, v26
	v_mul_f32_e32 v27, 0x3fb8aa3b, v27
	s_ashr_i32 s81, s80, 31
	v_exp_f32_e32 v24, v24
	v_exp_f32_e32 v25, v25
	v_exp_f32_e32 v26, v26
	v_exp_f32_e32 v27, v27
	v_mul_f32_e32 v28, 0x3fb8aa3b, v28
	v_mul_f32_e32 v29, 0x3fb8aa3b, v29
	v_mul_f32_e32 v30, 0x3fb8aa3b, v30
	v_mul_f32_e32 v31, 0x3fb8aa3b, v31
	s_lshl_b64 s[42:43], s[80:81], 9
	v_exp_f32_e32 v28, v28
	v_exp_f32_e32 v29, v29
	v_exp_f32_e32 v30, v30
	v_exp_f32_e32 v31, v31
	v_mul_f32_e32 v20, 0x3fb8aa3b, v20
	v_mul_f32_e32 v21, 0x3fb8aa3b, v21
	v_mul_f32_e32 v22, 0x3fb8aa3b, v22
	v_mul_f32_e32 v23, 0x3fb8aa3b, v23
	v_lshl_add_u64 v[36:37], v[54:55], 0, s[42:43]
	v_exp_f32_e32 v20, v20
	v_exp_f32_e32 v21, v21
	v_exp_f32_e32 v22, v22
	v_exp_f32_e32 v23, v23
	global_store_dwordx4 v[36:37], v[32:35], off
	global_store_dwordx4 v[36:37], v[24:27], off offset:16
	global_store_dwordx4 v[36:37], v[28:31], off offset:32
	global_store_dwordx4 v[36:37], v[20:23], off offset:48
